# v21 + saddr-form LDS-DMA also in the P2, P8 and P13 K-loops
# baseline (speedup 1.0000x reference)
.LBB0_425:
	v_add_u32_e32 v140, s67, v143
	ds_read_b128 v[146:149], v140
	ds_read_b128 v[150:153], v140 offset:1024
	ds_read_b128 v[154:157], v140 offset:2048
	ds_read_b128 v[158:161], v140 offset:3072
	v_add_u32_e32 v140, s68, v143
	ds_read_b128 v[162:165], v140
	ds_read_b128 v[166:169], v140 offset:1024
	ds_read_b128 v[170:173], v140 offset:2048
	ds_read_b128 v[174:177], v140 offset:3072
	s_add_i32 s13, s13, 2
	s_lshr_b32 s0, s13, 6
	s_mul_hi_u32 s1, s0, 0x8200000
	s_mul_i32 s0, s0, 0x8200000
	s_add_u32 s0, s46, s0
	s_addc_u32 s1, s47, s1
	s_and_b32 s35, s35, 0x1f00
	s_add_u32 s0, s0, s35
	s_addc_u32 s1, s1, 0
	s_add_u32 s0, s0, 0x100080
	s_addc_u32 s1, s1, 0
	s_add_i32 m0, s43, 0xc000
	ds_read_b128 v[178:181], v145
	ds_read_b128 v[182:185], v145 offset:1024
	ds_read_b128 v[186:189], v145 offset:2048
	ds_read_b128 v[190:193], v145 offset:3072
	ds_read_b128 v[194:197], v145 offset:4096
	ds_read_b128 v[198:201], v145 offset:5120
	ds_read_b128 v[202:205], v145 offset:6144
	ds_read_b128 v[206:209], v145 offset:7168
	global_load_lds_dwordx4 v128, s[0:1]
	s_add_i32 m0, s43, 0xe000
	s_nop 0
	global_load_lds_dwordx4 v132, s[0:1]
	s_waitcnt vmcnt(8)
	s_waitcnt lgkmcnt(0)
	s_setprio 3
	s_barrier
	v_mfma_f32_16x16x32_bf16 v[124:127], v[146:149], v[178:181], v[124:127]
	v_mfma_f32_16x16x32_bf16 v[120:123], v[154:157], v[178:181], v[120:123]
	v_mfma_f32_16x16x32_bf16 v[116:119], v[146:149], v[186:189], v[116:119]
	v_mfma_f32_16x16x32_bf16 v[108:111], v[154:157], v[186:189], v[108:111]
	v_mfma_f32_16x16x32_bf16 v[100:103], v[146:149], v[194:197], v[100:103]
	v_mfma_f32_16x16x32_bf16 v[92:95], v[154:157], v[194:197], v[92:95]
	v_mfma_f32_16x16x32_bf16 v[84:87], v[146:149], v[202:205], v[84:87]
	v_mfma_f32_16x16x32_bf16 v[76:79], v[154:157], v[202:205], v[76:79]
	v_mfma_f32_16x16x32_bf16 v[124:127], v[150:153], v[182:185], v[124:127]
	v_mfma_f32_16x16x32_bf16 v[120:123], v[158:161], v[182:185], v[120:123]
	v_mfma_f32_16x16x32_bf16 v[116:119], v[150:153], v[190:193], v[116:119]
	v_mfma_f32_16x16x32_bf16 v[108:111], v[158:161], v[190:193], v[108:111]
	v_mfma_f32_16x16x32_bf16 v[100:103], v[150:153], v[198:201], v[100:103]
	v_mfma_f32_16x16x32_bf16 v[92:95], v[158:161], v[198:201], v[92:95]
	v_mfma_f32_16x16x32_bf16 v[84:87], v[150:153], v[206:209], v[84:87]
	v_mfma_f32_16x16x32_bf16 v[76:79], v[158:161], v[206:209], v[76:79]
	s_setprio 0
	s_setprio 3
	v_mfma_f32_16x16x32_bf16 v[112:115], v[162:165], v[178:181], v[112:115]
	v_mfma_f32_16x16x32_bf16 v[104:107], v[170:173], v[178:181], v[104:107]
	v_mfma_f32_16x16x32_bf16 v[96:99], v[162:165], v[186:189], v[96:99]
	v_mfma_f32_16x16x32_bf16 v[88:91], v[170:173], v[186:189], v[88:91]
	v_mfma_f32_16x16x32_bf16 v[80:83], v[162:165], v[194:197], v[80:83]
	v_mfma_f32_16x16x32_bf16 v[72:75], v[170:173], v[194:197], v[72:75]
	v_mfma_f32_16x16x32_bf16 v[68:71], v[162:165], v[202:205], v[68:71]
	v_mfma_f32_16x16x32_bf16 v[64:67], v[170:173], v[202:205], v[64:67]
	v_mfma_f32_16x16x32_bf16 v[112:115], v[166:169], v[182:185], v[112:115]
	v_mfma_f32_16x16x32_bf16 v[104:107], v[174:177], v[182:185], v[104:107]
	v_mfma_f32_16x16x32_bf16 v[96:99], v[166:169], v[190:193], v[96:99]
	v_mfma_f32_16x16x32_bf16 v[88:91], v[174:177], v[190:193], v[88:91]
	v_mfma_f32_16x16x32_bf16 v[80:83], v[166:169], v[198:201], v[80:83]
	v_mfma_f32_16x16x32_bf16 v[72:75], v[174:177], v[198:201], v[72:75]
	v_mfma_f32_16x16x32_bf16 v[68:71], v[166:169], v[206:209], v[68:71]
	v_mfma_f32_16x16x32_bf16 v[64:67], v[174:177], v[206:209], v[64:67]
	s_barrier
	s_setprio 0
	s_add_i32 s0, s67, s59
	v_lshl_add_u64 v[140:141], s[52:53], 0, v[130:131]
	s_mov_b32 m0, s0
	ds_read_b128 v[178:181], v145 offset:16384
	ds_read_b128 v[182:185], v145 offset:17408
	ds_read_b128 v[186:189], v145 offset:18432
	ds_read_b128 v[190:193], v145 offset:19456
	ds_read_b128 v[194:197], v145 offset:20480
	ds_read_b128 v[198:201], v145 offset:21504
	ds_read_b128 v[202:205], v145 offset:22528
	ds_read_b128 v[206:209], v145 offset:23552
	global_load_lds_dwordx4 v[140:141], off
	s_add_i32 m0, s0, 0x2000
	s_add_u32 s0, s52, 0x100000
	v_lshl_add_u64 v[210:211], s[52:53], 0, v[134:135]
	s_addc_u32 s1, s53, 0
	s_add_i32 s35, s68, s59
	global_load_lds_dwordx4 v[210:211], off
	s_mov_b32 m0, s35
	v_lshl_add_u64 v[214:215], s[54:55], 0, v[132:133]
	global_load_lds_dwordx4 v130, s[0:1]
	s_add_i32 m0, s35, 0x2000
	s_nop 0
	global_load_lds_dwordx4 v134, s[0:1]
	v_lshl_add_u64 v[212:213], s[54:55], 0, v[128:129]
	s_mov_b32 m0, s43
	s_nop 0
	global_load_lds_dwordx4 v[212:213], off
	s_mov_b32 m0, s62
	s_nop 0
	global_load_lds_dwordx4 v[214:215], off
	s_waitcnt vmcnt(8)
	s_waitcnt lgkmcnt(0)
	s_setprio 3
	s_barrier
	v_mfma_f32_16x16x32_bf16 v[60:63], v[146:149], v[178:181], v[60:63]
	v_mfma_f32_16x16x32_bf16 v[56:59], v[154:157], v[178:181], v[56:59]
	v_mfma_f32_16x16x32_bf16 v[52:55], v[146:149], v[186:189], v[52:55]
	v_mfma_f32_16x16x32_bf16 v[44:47], v[154:157], v[186:189], v[44:47]
	v_mfma_f32_16x16x32_bf16 v[36:39], v[146:149], v[194:197], v[36:39]
	v_mfma_f32_16x16x32_bf16 v[28:31], v[154:157], v[194:197], v[28:31]
	v_mfma_f32_16x16x32_bf16 v[20:23], v[146:149], v[202:205], v[20:23]
	v_mfma_f32_16x16x32_bf16 v[12:15], v[154:157], v[202:205], v[12:15]
	v_mfma_f32_16x16x32_bf16 v[60:63], v[150:153], v[182:185], v[60:63]
	v_mfma_f32_16x16x32_bf16 v[56:59], v[158:161], v[182:185], v[56:59]
	v_mfma_f32_16x16x32_bf16 v[52:55], v[150:153], v[190:193], v[52:55]
	v_mfma_f32_16x16x32_bf16 v[44:47], v[158:161], v[190:193], v[44:47]
	v_mfma_f32_16x16x32_bf16 v[36:39], v[150:153], v[198:201], v[36:39]
	v_mfma_f32_16x16x32_bf16 v[28:31], v[158:161], v[198:201], v[28:31]
	v_mfma_f32_16x16x32_bf16 v[20:23], v[150:153], v[206:209], v[20:23]
	v_mfma_f32_16x16x32_bf16 v[12:15], v[158:161], v[206:209], v[12:15]
	s_setprio 0
	s_setprio 3
	v_mfma_f32_16x16x32_bf16 v[48:51], v[162:165], v[178:181], v[48:51]
	v_mfma_f32_16x16x32_bf16 v[40:43], v[170:173], v[178:181], v[40:43]
	v_mfma_f32_16x16x32_bf16 v[32:35], v[162:165], v[186:189], v[32:35]
	v_mfma_f32_16x16x32_bf16 v[24:27], v[170:173], v[186:189], v[24:27]
	v_mfma_f32_16x16x32_bf16 v[16:19], v[162:165], v[194:197], v[16:19]
	v_mfma_f32_16x16x32_bf16 v[8:11], v[170:173], v[194:197], v[8:11]
	v_mfma_f32_16x16x32_bf16 v[4:7], v[162:165], v[202:205], v[4:7]
	v_mfma_f32_16x16x32_bf16 v[0:3], v[170:173], v[202:205], v[0:3]
	v_mfma_f32_16x16x32_bf16 v[48:51], v[166:169], v[182:185], v[48:51]
	v_mfma_f32_16x16x32_bf16 v[40:43], v[174:177], v[182:185], v[40:43]
	v_mfma_f32_16x16x32_bf16 v[32:35], v[166:169], v[190:193], v[32:35]
	v_mfma_f32_16x16x32_bf16 v[24:27], v[174:177], v[190:193], v[24:27]
	v_mfma_f32_16x16x32_bf16 v[16:19], v[166:169], v[198:201], v[16:19]
	v_mfma_f32_16x16x32_bf16 v[8:11], v[174:177], v[198:201], v[8:11]
	v_mfma_f32_16x16x32_bf16 v[4:7], v[166:169], v[206:209], v[4:7]
	v_mfma_f32_16x16x32_bf16 v[0:3], v[174:177], v[206:209], v[0:3]
	s_barrier
	s_setprio 0
	s_add_i32 s35, 0, 0x18000
	s_add_i32 s37, 0, 0x1c000
	v_add_u32_e32 v158, s35, v143
	v_add_u32_e32 v174, s37, v143
	ds_read_b128 v[146:149], v158
	ds_read_b128 v[150:153], v158 offset:1024
	ds_read_b128 v[154:157], v158 offset:2048
	ds_read_b128 v[158:161], v158 offset:3072
	ds_read_b128 v[162:165], v174
	ds_read_b128 v[166:169], v174 offset:1024
	ds_read_b128 v[170:173], v174 offset:2048
	ds_read_b128 v[174:177], v174 offset:3072
	s_add_u32 s0, s54, 0x100000
	s_addc_u32 s1, s55, 0
	s_mov_b32 m0, s63
	ds_read_b128 v[178:181], v145 offset:32768
	ds_read_b128 v[182:185], v145 offset:33792
	ds_read_b128 v[186:189], v145 offset:34816
	ds_read_b128 v[190:193], v145 offset:35840
	ds_read_b128 v[194:197], v145 offset:36864
	ds_read_b128 v[198:201], v145 offset:37888
	ds_read_b128 v[202:205], v145 offset:38912
	ds_read_b128 v[206:209], v145 offset:39936
	global_load_lds_dwordx4 v128, s[0:1]
	s_mov_b32 m0, s64
	s_nop 0
	global_load_lds_dwordx4 v132, s[0:1]
	s_waitcnt vmcnt(8)
	s_waitcnt lgkmcnt(0)
	s_setprio 3
	s_barrier
	v_mfma_f32_16x16x32_bf16 v[124:127], v[146:149], v[178:181], v[124:127]
	v_mfma_f32_16x16x32_bf16 v[120:123], v[154:157], v[178:181], v[120:123]
	v_mfma_f32_16x16x32_bf16 v[116:119], v[146:149], v[186:189], v[116:119]
	v_mfma_f32_16x16x32_bf16 v[108:111], v[154:157], v[186:189], v[108:111]
	v_mfma_f32_16x16x32_bf16 v[100:103], v[146:149], v[194:197], v[100:103]
	v_mfma_f32_16x16x32_bf16 v[92:95], v[154:157], v[194:197], v[92:95]
	v_mfma_f32_16x16x32_bf16 v[84:87], v[146:149], v[202:205], v[84:87]
	v_mfma_f32_16x16x32_bf16 v[76:79], v[154:157], v[202:205], v[76:79]
	v_mfma_f32_16x16x32_bf16 v[124:127], v[150:153], v[182:185], v[124:127]
	v_mfma_f32_16x16x32_bf16 v[120:123], v[158:161], v[182:185], v[120:123]
	v_mfma_f32_16x16x32_bf16 v[116:119], v[150:153], v[190:193], v[116:119]
	v_mfma_f32_16x16x32_bf16 v[108:111], v[158:161], v[190:193], v[108:111]
	v_mfma_f32_16x16x32_bf16 v[100:103], v[150:153], v[198:201], v[100:103]
	v_mfma_f32_16x16x32_bf16 v[92:95], v[158:161], v[198:201], v[92:95]
	v_mfma_f32_16x16x32_bf16 v[84:87], v[150:153], v[206:209], v[84:87]
	v_mfma_f32_16x16x32_bf16 v[76:79], v[158:161], v[206:209], v[76:79]
	s_setprio 0
	s_setprio 3
	v_mfma_f32_16x16x32_bf16 v[112:115], v[162:165], v[178:181], v[112:115]
	v_mfma_f32_16x16x32_bf16 v[104:107], v[170:173], v[178:181], v[104:107]
	v_mfma_f32_16x16x32_bf16 v[96:99], v[162:165], v[186:189], v[96:99]
	v_mfma_f32_16x16x32_bf16 v[88:91], v[170:173], v[186:189], v[88:91]
	v_mfma_f32_16x16x32_bf16 v[80:83], v[162:165], v[194:197], v[80:83]
	v_mfma_f32_16x16x32_bf16 v[72:75], v[170:173], v[194:197], v[72:75]
	v_mfma_f32_16x16x32_bf16 v[68:71], v[162:165], v[202:205], v[68:71]
	v_mfma_f32_16x16x32_bf16 v[64:67], v[170:173], v[202:205], v[64:67]
	v_mfma_f32_16x16x32_bf16 v[112:115], v[166:169], v[182:185], v[112:115]
	v_mfma_f32_16x16x32_bf16 v[104:107], v[174:177], v[182:185], v[104:107]
	v_mfma_f32_16x16x32_bf16 v[96:99], v[166:169], v[190:193], v[96:99]
	v_mfma_f32_16x16x32_bf16 v[88:91], v[174:177], v[190:193], v[88:91]
	v_mfma_f32_16x16x32_bf16 v[80:83], v[166:169], v[198:201], v[80:83]
	v_mfma_f32_16x16x32_bf16 v[72:75], v[174:177], v[198:201], v[72:75]
	v_mfma_f32_16x16x32_bf16 v[68:71], v[166:169], v[206:209], v[68:71]
	v_mfma_f32_16x16x32_bf16 v[64:67], v[174:177], v[206:209], v[64:67]
	s_barrier
	s_setprio 0
	s_add_i32 s0, s35, s59
	v_lshl_add_u64 v[140:141], v[140:141], 0, s[14:15]
	s_mov_b32 m0, s0
	ds_read_b128 v[178:181], v145 offset:49152
	ds_read_b128 v[182:185], v145 offset:50176
	ds_read_b128 v[186:189], v145 offset:51200
	ds_read_b128 v[190:193], v145 offset:52224
	ds_read_b128 v[194:197], v145 offset:53248
	ds_read_b128 v[198:201], v145 offset:54272
	ds_read_b128 v[202:205], v145 offset:55296
	ds_read_b128 v[206:209], v145 offset:56320
	global_load_lds_dwordx4 v[140:141], off
	s_add_i32 m0, s0, 0x2000
	s_add_u32 s0, s52, 0x100080
	v_lshl_add_u64 v[140:141], v[210:211], 0, s[14:15]
	s_addc_u32 s1, s53, 0
	s_add_i32 s35, s37, s59
	global_load_lds_dwordx4 v[140:141], off
	s_mov_b32 m0, s35
	s_nop 0
	global_load_lds_dwordx4 v130, s[0:1]
	s_add_i32 m0, s35, 0x2000
	s_nop 0
	global_load_lds_dwordx4 v134, s[0:1]
	v_lshl_add_u64 v[140:141], v[212:213], 0, s[14:15]
	s_mov_b32 m0, s60
	s_nop 0
	global_load_lds_dwordx4 v[140:141], off
	v_lshl_add_u64 v[140:141], v[214:215], 0, s[14:15]
	s_mov_b32 m0, s65
	s_nop 0
	global_load_lds_dwordx4 v[140:141], off
	s_waitcnt vmcnt(8)
	s_waitcnt lgkmcnt(0)
	s_setprio 3
	s_barrier
	v_mfma_f32_16x16x32_bf16 v[60:63], v[146:149], v[178:181], v[60:63]
	v_mfma_f32_16x16x32_bf16 v[56:59], v[154:157], v[178:181], v[56:59]
	v_mfma_f32_16x16x32_bf16 v[52:55], v[146:149], v[186:189], v[52:55]
	v_mfma_f32_16x16x32_bf16 v[44:47], v[154:157], v[186:189], v[44:47]
	v_mfma_f32_16x16x32_bf16 v[36:39], v[146:149], v[194:197], v[36:39]
	v_mfma_f32_16x16x32_bf16 v[28:31], v[154:157], v[194:197], v[28:31]
	v_mfma_f32_16x16x32_bf16 v[20:23], v[146:149], v[202:205], v[20:23]
	v_mfma_f32_16x16x32_bf16 v[12:15], v[154:157], v[202:205], v[12:15]
	v_mfma_f32_16x16x32_bf16 v[60:63], v[150:153], v[182:185], v[60:63]
	v_mfma_f32_16x16x32_bf16 v[56:59], v[158:161], v[182:185], v[56:59]
	v_mfma_f32_16x16x32_bf16 v[52:55], v[150:153], v[190:193], v[52:55]
	v_mfma_f32_16x16x32_bf16 v[44:47], v[158:161], v[190:193], v[44:47]
	v_mfma_f32_16x16x32_bf16 v[36:39], v[150:153], v[198:201], v[36:39]
	v_mfma_f32_16x16x32_bf16 v[28:31], v[158:161], v[198:201], v[28:31]
	v_mfma_f32_16x16x32_bf16 v[20:23], v[150:153], v[206:209], v[20:23]
	v_mfma_f32_16x16x32_bf16 v[12:15], v[158:161], v[206:209], v[12:15]
	s_setprio 0
	s_setprio 3
	v_mfma_f32_16x16x32_bf16 v[48:51], v[162:165], v[178:181], v[48:51]
	v_mfma_f32_16x16x32_bf16 v[40:43], v[170:173], v[178:181], v[40:43]
	v_mfma_f32_16x16x32_bf16 v[32:35], v[162:165], v[186:189], v[32:35]
	v_mfma_f32_16x16x32_bf16 v[24:27], v[170:173], v[186:189], v[24:27]
	v_mfma_f32_16x16x32_bf16 v[16:19], v[162:165], v[194:197], v[16:19]
	v_mfma_f32_16x16x32_bf16 v[8:11], v[170:173], v[194:197], v[8:11]
	v_mfma_f32_16x16x32_bf16 v[4:7], v[162:165], v[202:205], v[4:7]
	v_mfma_f32_16x16x32_bf16 v[0:3], v[170:173], v[202:205], v[0:3]
	v_mfma_f32_16x16x32_bf16 v[48:51], v[166:169], v[182:185], v[48:51]
	v_mfma_f32_16x16x32_bf16 v[40:43], v[174:177], v[182:185], v[40:43]
	v_mfma_f32_16x16x32_bf16 v[32:35], v[166:169], v[190:193], v[32:35]
	v_mfma_f32_16x16x32_bf16 v[24:27], v[174:177], v[190:193], v[24:27]
	v_mfma_f32_16x16x32_bf16 v[16:19], v[166:169], v[198:201], v[16:19]
	v_mfma_f32_16x16x32_bf16 v[8:11], v[174:177], v[198:201], v[8:11]
	v_mfma_f32_16x16x32_bf16 v[4:7], v[166:169], v[206:209], v[4:7]
	v_mfma_f32_16x16x32_bf16 v[0:3], v[174:177], v[206:209], v[0:3]
	s_barrier
	s_setprio 0
	s_cmpk_gt_u32 s13, 0xa9
	s_mov_b32 s35, s4
	s_cbranch_scc1 .LBB0_432

.LBB0_1544:
	v_add_u32_e32 v1, s88, v155
	ds_read_b128 v[158:161], v1
	ds_read_b128 v[162:165], v1 offset:1024
	ds_read_b128 v[166:169], v1 offset:2048
	ds_read_b128 v[170:173], v1 offset:3072
	v_add_u32_e32 v1, s89, v155
	s_add_u32 s0, s50, s6
	ds_read_b128 v[174:177], v1
	ds_read_b128 v[178:181], v1 offset:1024
	ds_read_b128 v[182:185], v1 offset:2048
	ds_read_b128 v[186:189], v1 offset:3072
	s_addc_u32 s1, s51, s7
	s_add_u32 s0, s0, 0x100
	s_addc_u32 s1, s1, 0
	s_add_u32 s26, s96, s6
	s_addc_u32 s27, s97, s7
	s_cmpk_eq_i32 s6, 0x1f00
	s_cselect_b32 s55, s47, s1
	s_cselect_b32 s54, s46, s0
	s_cselect_b32 s53, s92, s27
	s_cselect_b32 s52, s93, s26
	v_lshl_add_u64 v[2:3], v[148:149], 0, s[6:7]
	s_add_i32 m0, s61, 0xc000
	ds_read_b128 v[190:193], v157
	ds_read_b128 v[194:197], v157 offset:1024
	ds_read_b128 v[198:201], v157 offset:2048
	ds_read_b128 v[210:213], v157 offset:3072
	ds_read_b128 v[214:217], v157 offset:4096
	ds_read_b128 v[218:221], v157 offset:5120
	ds_read_b128 v[222:225], v157 offset:6144
	ds_read_b128 v[226:229], v157 offset:7168
	global_load_lds_dwordx4 v[2:3], off
	v_lshl_add_u64 v[2:3], v[150:151], 0, s[6:7]
	s_add_i32 m0, s61, 0xe000
	s_nop 0
	global_load_lds_dwordx4 v[2:3], off
	s_waitcnt vmcnt(8)
	s_waitcnt lgkmcnt(0)
	s_setprio 3
	s_barrier
	v_mfma_f32_16x16x32_bf16 v[128:131], v[158:161], v[190:193], v[128:131]
	v_mfma_f32_16x16x32_bf16 v[124:127], v[166:169], v[190:193], v[124:127]
	v_mfma_f32_16x16x32_bf16 v[112:115], v[158:161], v[198:201], v[112:115]
	v_mfma_f32_16x16x32_bf16 v[108:111], v[166:169], v[198:201], v[108:111]
	v_mfma_f32_16x16x32_bf16 v[96:99], v[158:161], v[214:217], v[96:99]
	v_mfma_f32_16x16x32_bf16 v[92:95], v[166:169], v[214:217], v[92:95]
	v_mfma_f32_16x16x32_bf16 v[80:83], v[158:161], v[222:225], v[80:83]
	v_mfma_f32_16x16x32_bf16 v[76:79], v[166:169], v[222:225], v[76:79]
	v_mfma_f32_16x16x32_bf16 v[128:131], v[162:165], v[194:197], v[128:131]
	v_mfma_f32_16x16x32_bf16 v[124:127], v[170:173], v[194:197], v[124:127]
	v_mfma_f32_16x16x32_bf16 v[112:115], v[162:165], v[210:213], v[112:115]
	v_mfma_f32_16x16x32_bf16 v[108:111], v[170:173], v[210:213], v[108:111]
	v_mfma_f32_16x16x32_bf16 v[96:99], v[162:165], v[218:221], v[96:99]
	v_mfma_f32_16x16x32_bf16 v[92:95], v[170:173], v[218:221], v[92:95]
	v_mfma_f32_16x16x32_bf16 v[80:83], v[162:165], v[226:229], v[80:83]
	v_mfma_f32_16x16x32_bf16 v[76:79], v[170:173], v[226:229], v[76:79]
	s_setprio 0
	s_setprio 3
	v_mfma_f32_16x16x32_bf16 v[120:123], v[174:177], v[190:193], v[120:123]
	v_mfma_f32_16x16x32_bf16 v[116:119], v[182:185], v[190:193], v[116:119]
	v_mfma_f32_16x16x32_bf16 v[104:107], v[174:177], v[198:201], v[104:107]
	v_mfma_f32_16x16x32_bf16 v[100:103], v[182:185], v[198:201], v[100:103]
	v_mfma_f32_16x16x32_bf16 v[88:91], v[174:177], v[214:217], v[88:91]
	v_mfma_f32_16x16x32_bf16 v[84:87], v[182:185], v[214:217], v[84:87]
	v_mfma_f32_16x16x32_bf16 v[72:75], v[174:177], v[222:225], v[72:75]
	v_mfma_f32_16x16x32_bf16 v[68:71], v[182:185], v[222:225], v[68:71]
	v_mfma_f32_16x16x32_bf16 v[120:123], v[178:181], v[194:197], v[120:123]
	v_mfma_f32_16x16x32_bf16 v[116:119], v[186:189], v[194:197], v[116:119]
	v_mfma_f32_16x16x32_bf16 v[104:107], v[178:181], v[210:213], v[104:107]
	v_mfma_f32_16x16x32_bf16 v[100:103], v[186:189], v[210:213], v[100:103]
	v_mfma_f32_16x16x32_bf16 v[88:91], v[178:181], v[218:221], v[88:91]
	v_mfma_f32_16x16x32_bf16 v[84:87], v[186:189], v[218:221], v[84:87]
	v_mfma_f32_16x16x32_bf16 v[72:75], v[178:181], v[226:229], v[72:75]
	v_mfma_f32_16x16x32_bf16 v[68:71], v[186:189], v[226:229], v[68:71]
	s_barrier
	s_setprio 0
	s_add_i32 s0, s88, s60
	v_lshl_add_u64 v[202:203], s[52:53], 0, v[134:135]
	s_mov_b32 m0, s0
	ds_read_b128 v[190:193], v157 offset:16384
	ds_read_b128 v[194:197], v157 offset:17408
	ds_read_b128 v[198:201], v157 offset:18432
	ds_read_b128 v[210:213], v157 offset:19456
	ds_read_b128 v[214:217], v157 offset:20480
	ds_read_b128 v[218:221], v157 offset:21504
	ds_read_b128 v[222:225], v157 offset:22528
	ds_read_b128 v[226:229], v157 offset:23552
	global_load_lds_dwordx4 v[202:203], off
	s_add_i32 m0, s0, 0x2000
	s_add_u32 s0, s52, 0x100000
	v_lshl_add_u64 v[230:231], s[52:53], 0, v[138:139]
	s_addc_u32 s1, s53, 0
	s_add_i32 s26, s89, s60
	global_load_lds_dwordx4 v[230:231], off
	s_mov_b32 m0, s26
	v_lshl_add_u64 v[232:233], s[54:55], 0, v[132:133]
	global_load_lds_dwordx4 v134, s[0:1]
	s_add_i32 m0, s26, 0x2000
	v_lshl_add_u64 v[234:235], s[54:55], 0, v[136:137]
	global_load_lds_dwordx4 v138, s[0:1]
	s_mov_b32 m0, s61
	s_nop 0
	global_load_lds_dwordx4 v[232:233], off
	s_mov_b32 m0, s62
	s_nop 0
	global_load_lds_dwordx4 v[234:235], off
	s_waitcnt vmcnt(8)
	s_waitcnt lgkmcnt(0)
	s_setprio 3
	s_barrier
	v_mfma_f32_16x16x32_bf16 v[64:67], v[158:161], v[190:193], v[64:67]
	v_mfma_f32_16x16x32_bf16 v[60:63], v[166:169], v[190:193], v[60:63]
	v_mfma_f32_16x16x32_bf16 v[48:51], v[158:161], v[198:201], v[48:51]
	v_mfma_f32_16x16x32_bf16 v[44:47], v[166:169], v[198:201], v[44:47]
	v_mfma_f32_16x16x32_bf16 v[32:35], v[158:161], v[214:217], v[32:35]
	v_mfma_f32_16x16x32_bf16 v[28:31], v[166:169], v[214:217], v[28:31]
	v_mfma_f32_16x16x32_bf16 v[16:19], v[158:161], v[222:225], v[16:19]
	v_mfma_f32_16x16x32_bf16 v[12:15], v[166:169], v[222:225], v[12:15]
	v_mfma_f32_16x16x32_bf16 v[64:67], v[162:165], v[194:197], v[64:67]
	v_mfma_f32_16x16x32_bf16 v[60:63], v[170:173], v[194:197], v[60:63]
	v_mfma_f32_16x16x32_bf16 v[48:51], v[162:165], v[210:213], v[48:51]
	v_mfma_f32_16x16x32_bf16 v[44:47], v[170:173], v[210:213], v[44:47]
	v_mfma_f32_16x16x32_bf16 v[32:35], v[162:165], v[218:221], v[32:35]
	v_mfma_f32_16x16x32_bf16 v[28:31], v[170:173], v[218:221], v[28:31]
	v_mfma_f32_16x16x32_bf16 v[16:19], v[162:165], v[226:229], v[16:19]
	v_mfma_f32_16x16x32_bf16 v[12:15], v[170:173], v[226:229], v[12:15]
	s_setprio 0
	s_setprio 3
	v_mfma_f32_16x16x32_bf16 v[56:59], v[174:177], v[190:193], v[56:59]
	v_mfma_f32_16x16x32_bf16 v[52:55], v[182:185], v[190:193], v[52:55]
	v_mfma_f32_16x16x32_bf16 v[40:43], v[174:177], v[198:201], v[40:43]
	v_mfma_f32_16x16x32_bf16 v[36:39], v[182:185], v[198:201], v[36:39]
	v_mfma_f32_16x16x32_bf16 v[24:27], v[174:177], v[214:217], v[24:27]
	v_mfma_f32_16x16x32_bf16 v[20:23], v[182:185], v[214:217], v[20:23]
	v_mfma_f32_16x16x32_bf16 v[8:11], v[174:177], v[222:225], v[8:11]
	v_mfma_f32_16x16x32_bf16 v[2:5], v[182:185], v[222:225], v[4:7]
	v_mfma_f32_16x16x32_bf16 v[56:59], v[178:181], v[194:197], v[56:59]
	v_mfma_f32_16x16x32_bf16 v[52:55], v[186:189], v[194:197], v[52:55]
	v_mfma_f32_16x16x32_bf16 v[40:43], v[178:181], v[210:213], v[40:43]
	v_mfma_f32_16x16x32_bf16 v[36:39], v[186:189], v[210:213], v[36:39]
	v_mfma_f32_16x16x32_bf16 v[24:27], v[178:181], v[218:221], v[24:27]
	v_mfma_f32_16x16x32_bf16 v[20:23], v[186:189], v[218:221], v[20:23]
	v_mfma_f32_16x16x32_bf16 v[8:11], v[178:181], v[226:229], v[8:11]
	v_mfma_f32_16x16x32_bf16 v[2:5], v[186:189], v[226:229], v[2:5]
	s_barrier
	s_setprio 0
	s_add_i32 s26, 0, 0x18000
	v_add_u32_e32 v1, s26, v155
	s_add_i32 s27, 0, 0x1c000
	ds_read_b128 v[158:161], v1
	ds_read_b128 v[162:165], v1 offset:1024
	ds_read_b128 v[166:169], v1 offset:2048
	ds_read_b128 v[170:173], v1 offset:3072
	v_add_u32_e32 v1, s27, v155
	ds_read_b128 v[174:177], v1
	ds_read_b128 v[178:181], v1 offset:1024
	ds_read_b128 v[182:185], v1 offset:2048
	ds_read_b128 v[186:189], v1 offset:3072
	s_add_u32 s0, s54, 0x180000
	s_addc_u32 s1, s55, 0
	s_mov_b32 m0, s63
	ds_read_b128 v[190:193], v157 offset:32768
	ds_read_b128 v[194:197], v157 offset:33792
	ds_read_b128 v[198:201], v157 offset:34816
	ds_read_b128 v[210:213], v157 offset:35840
	ds_read_b128 v[214:217], v157 offset:36864
	ds_read_b128 v[218:221], v157 offset:37888
	ds_read_b128 v[222:225], v157 offset:38912
	ds_read_b128 v[226:229], v157 offset:39936
	global_load_lds_dwordx4 v132, s[0:1]
	s_mov_b32 m0, s64
	s_nop 0
	global_load_lds_dwordx4 v136, s[0:1]
	s_waitcnt vmcnt(8)
	s_waitcnt lgkmcnt(0)
	s_setprio 3
	s_barrier
	v_mfma_f32_16x16x32_bf16 v[128:131], v[158:161], v[190:193], v[128:131]
	v_mfma_f32_16x16x32_bf16 v[124:127], v[166:169], v[190:193], v[124:127]
	v_mfma_f32_16x16x32_bf16 v[112:115], v[158:161], v[198:201], v[112:115]
	v_mfma_f32_16x16x32_bf16 v[108:111], v[166:169], v[198:201], v[108:111]
	v_mfma_f32_16x16x32_bf16 v[96:99], v[158:161], v[214:217], v[96:99]
	v_mfma_f32_16x16x32_bf16 v[92:95], v[166:169], v[214:217], v[92:95]
	v_mfma_f32_16x16x32_bf16 v[80:83], v[158:161], v[222:225], v[80:83]
	v_mfma_f32_16x16x32_bf16 v[76:79], v[166:169], v[222:225], v[76:79]
	v_mfma_f32_16x16x32_bf16 v[128:131], v[162:165], v[194:197], v[128:131]
	v_mfma_f32_16x16x32_bf16 v[124:127], v[170:173], v[194:197], v[124:127]
	v_mfma_f32_16x16x32_bf16 v[112:115], v[162:165], v[210:213], v[112:115]
	v_mfma_f32_16x16x32_bf16 v[108:111], v[170:173], v[210:213], v[108:111]
	v_mfma_f32_16x16x32_bf16 v[96:99], v[162:165], v[218:221], v[96:99]
	v_mfma_f32_16x16x32_bf16 v[92:95], v[170:173], v[218:221], v[92:95]
	v_mfma_f32_16x16x32_bf16 v[80:83], v[162:165], v[226:229], v[80:83]
	v_mfma_f32_16x16x32_bf16 v[76:79], v[170:173], v[226:229], v[76:79]
	s_setprio 0
	s_setprio 3
	v_mfma_f32_16x16x32_bf16 v[120:123], v[174:177], v[190:193], v[120:123]
	v_mfma_f32_16x16x32_bf16 v[116:119], v[182:185], v[190:193], v[116:119]
	v_mfma_f32_16x16x32_bf16 v[104:107], v[174:177], v[198:201], v[104:107]
	v_mfma_f32_16x16x32_bf16 v[100:103], v[182:185], v[198:201], v[100:103]
	v_mfma_f32_16x16x32_bf16 v[88:91], v[174:177], v[214:217], v[88:91]
	v_mfma_f32_16x16x32_bf16 v[84:87], v[182:185], v[214:217], v[84:87]
	v_mfma_f32_16x16x32_bf16 v[72:75], v[174:177], v[222:225], v[72:75]
	v_mfma_f32_16x16x32_bf16 v[68:71], v[182:185], v[222:225], v[68:71]
	v_mfma_f32_16x16x32_bf16 v[120:123], v[178:181], v[194:197], v[120:123]
	v_mfma_f32_16x16x32_bf16 v[116:119], v[186:189], v[194:197], v[116:119]
	v_mfma_f32_16x16x32_bf16 v[104:107], v[178:181], v[210:213], v[104:107]
	v_mfma_f32_16x16x32_bf16 v[100:103], v[186:189], v[210:213], v[100:103]
	v_mfma_f32_16x16x32_bf16 v[88:91], v[178:181], v[218:221], v[88:91]
	v_mfma_f32_16x16x32_bf16 v[84:87], v[186:189], v[218:221], v[84:87]
	v_mfma_f32_16x16x32_bf16 v[72:75], v[178:181], v[226:229], v[72:75]
	v_mfma_f32_16x16x32_bf16 v[68:71], v[186:189], v[226:229], v[68:71]
	s_barrier
	s_setprio 0
	s_add_i32 s0, s26, s60
	v_lshl_add_u64 v[6:7], v[202:203], 0, s[16:17]
	s_mov_b32 m0, s0
	ds_read_b128 v[190:193], v157 offset:49152
	ds_read_b128 v[194:197], v157 offset:50176
	ds_read_b128 v[198:201], v157 offset:51200
	ds_read_b128 v[210:213], v157 offset:52224
	ds_read_b128 v[214:217], v157 offset:53248
	ds_read_b128 v[218:221], v157 offset:54272
	ds_read_b128 v[222:225], v157 offset:55296
	ds_read_b128 v[226:229], v157 offset:56320
	global_load_lds_dwordx4 v[6:7], off
	s_add_i32 m0, s0, 0x2000
	s_add_u32 s0, s52, 0x100080
	v_lshl_add_u64 v[6:7], v[230:231], 0, s[16:17]
	s_addc_u32 s1, s53, 0
	s_add_i32 s26, s27, s60
	global_load_lds_dwordx4 v[6:7], off
	s_mov_b32 m0, s26
	s_nop 0
	global_load_lds_dwordx4 v134, s[0:1]
	s_add_i32 m0, s26, 0x2000
	s_nop 0
	global_load_lds_dwordx4 v138, s[0:1]
	v_lshl_add_u64 v[6:7], v[232:233], 0, s[16:17]
	s_mov_b32 m0, s68
	s_nop 0
	global_load_lds_dwordx4 v[6:7], off
	v_lshl_add_u64 v[6:7], v[234:235], 0, s[16:17]
	s_mov_b32 m0, s69
	s_nop 0
	global_load_lds_dwordx4 v[6:7], off
	s_waitcnt vmcnt(8)
	s_waitcnt lgkmcnt(0)
	s_setprio 3
	s_barrier
	v_mfma_f32_16x16x32_bf16 v[64:67], v[158:161], v[190:193], v[64:67]
	v_mfma_f32_16x16x32_bf16 v[60:63], v[166:169], v[190:193], v[60:63]
	v_mfma_f32_16x16x32_bf16 v[48:51], v[158:161], v[198:201], v[48:51]
	v_mfma_f32_16x16x32_bf16 v[44:47], v[166:169], v[198:201], v[44:47]
	v_mfma_f32_16x16x32_bf16 v[32:35], v[158:161], v[214:217], v[32:35]
	v_mfma_f32_16x16x32_bf16 v[28:31], v[166:169], v[214:217], v[28:31]
	v_mfma_f32_16x16x32_bf16 v[16:19], v[158:161], v[222:225], v[16:19]
	v_mfma_f32_16x16x32_bf16 v[12:15], v[166:169], v[222:225], v[12:15]
	v_mfma_f32_16x16x32_bf16 v[64:67], v[162:165], v[194:197], v[64:67]
	v_mfma_f32_16x16x32_bf16 v[60:63], v[170:173], v[194:197], v[60:63]
	v_mfma_f32_16x16x32_bf16 v[48:51], v[162:165], v[210:213], v[48:51]
	v_mfma_f32_16x16x32_bf16 v[44:47], v[170:173], v[210:213], v[44:47]
	v_mfma_f32_16x16x32_bf16 v[32:35], v[162:165], v[218:221], v[32:35]
	v_mfma_f32_16x16x32_bf16 v[28:31], v[170:173], v[218:221], v[28:31]
	v_mfma_f32_16x16x32_bf16 v[16:19], v[162:165], v[226:229], v[16:19]
	v_mfma_f32_16x16x32_bf16 v[12:15], v[170:173], v[226:229], v[12:15]
	s_setprio 0
	s_setprio 3
	v_mfma_f32_16x16x32_bf16 v[56:59], v[174:177], v[190:193], v[56:59]
	v_mfma_f32_16x16x32_bf16 v[52:55], v[182:185], v[190:193], v[52:55]
	v_mfma_f32_16x16x32_bf16 v[40:43], v[174:177], v[198:201], v[40:43]
	v_mfma_f32_16x16x32_bf16 v[36:39], v[182:185], v[198:201], v[36:39]
	v_mfma_f32_16x16x32_bf16 v[24:27], v[174:177], v[214:217], v[24:27]
	v_mfma_f32_16x16x32_bf16 v[20:23], v[182:185], v[214:217], v[20:23]
	v_mfma_f32_16x16x32_bf16 v[6:9], v[174:177], v[222:225], v[8:11]
	v_mfma_f32_16x16x32_bf16 v[2:5], v[182:185], v[222:225], v[2:5]
	v_mfma_f32_16x16x32_bf16 v[56:59], v[178:181], v[194:197], v[56:59]
	v_mfma_f32_16x16x32_bf16 v[52:55], v[186:189], v[194:197], v[52:55]
	v_mfma_f32_16x16x32_bf16 v[40:43], v[178:181], v[210:213], v[40:43]
	v_mfma_f32_16x16x32_bf16 v[36:39], v[186:189], v[210:213], v[36:39]
	v_mfma_f32_16x16x32_bf16 v[24:27], v[178:181], v[218:221], v[24:27]
	v_mfma_f32_16x16x32_bf16 v[20:23], v[186:189], v[218:221], v[20:23]
	v_mfma_f32_16x16x32_bf16 v[8:11], v[178:181], v[226:229], v[6:9]
	v_mfma_f32_16x16x32_bf16 v[4:7], v[186:189], v[226:229], v[2:5]
	s_barrier
	s_setprio 0
	s_add_u32 s6, s6, 0x100
	s_addc_u32 s7, s7, 0
	s_add_i32 s23, s23, 2
	s_cmp_gt_u32 s23, 61
	s_cbranch_scc1 .LBB0_1547

.LBB0_1974:
	v_add_u32_e32 v0, s65, v182
	v_add_u32_e32 v4, s66, v182
	ds_read_b128 v[24:27], v0
	ds_read_b128 v[28:31], v0 offset:1024
	ds_read_b128 v[16:19], v0 offset:2048
	ds_read_b128 v[20:23], v0 offset:3072
	ds_read_b128 v[8:11], v4
	ds_read_b128 v[12:15], v4 offset:1024
	ds_read_b128 v[0:3], v4 offset:2048
	ds_read_b128 v[4:7], v4 offset:3072
	s_add_i32 s35, s35, 2
	s_lshr_b32 s0, s35, 5
	s_mul_hi_u32 s1, s0, 0x4100000
	s_mul_i32 s0, s0, 0x4100000
	s_add_u32 s0, s46, s0
	s_addc_u32 s1, s47, s1
	s_and_b32 s37, s37, 0xf00
	s_add_u32 s0, s0, s37
	s_addc_u32 s1, s1, 0
	s_add_u32 s0, s0, 0x80080
	s_addc_u32 s1, s1, 0
	s_add_i32 m0, s43, 0xc000
	ds_read_b128 v[172:175], v184
	ds_read_b128 v[176:179], v184 offset:1024
	ds_read_b128 v[186:189], v184 offset:2048
	ds_read_b128 v[190:193], v184 offset:3072
	ds_read_b128 v[194:197], v184 offset:4096
	ds_read_b128 v[198:201], v184 offset:5120
	ds_read_b128 v[210:213], v184 offset:6144
	ds_read_b128 v[214:217], v184 offset:7168
	global_load_lds_dwordx4 v160, s[0:1]
	s_add_i32 m0, s43, 0xe000
	s_nop 0
	global_load_lds_dwordx4 v164, s[0:1]
	s_waitcnt vmcnt(8)
	s_waitcnt lgkmcnt(0)
	s_setprio 3
	s_barrier
	v_mfma_scale_f32_16x16x128_f8f6f4 v[156:159], v[24:31], v[172:179], v[156:159], v180, v180 op_sel_hi:[0,0,0]
	v_mfma_scale_f32_16x16x128_f8f6f4 v[152:155], v[16:23], v[172:179], v[152:155], v180, v180 op_sel_hi:[0,0,0]
	v_mfma_scale_f32_16x16x128_f8f6f4 v[144:147], v[24:31], v[186:193], v[144:147], v180, v180 op_sel_hi:[0,0,0]
	v_mfma_scale_f32_16x16x128_f8f6f4 v[136:139], v[16:23], v[186:193], v[136:139], v180, v180 op_sel_hi:[0,0,0]
	v_mfma_scale_f32_16x16x128_f8f6f4 v[128:131], v[24:31], v[194:201], v[128:131], v180, v180 op_sel_hi:[0,0,0]
	v_mfma_scale_f32_16x16x128_f8f6f4 v[120:123], v[16:23], v[194:201], v[120:123], v180, v180 op_sel_hi:[0,0,0]
	v_mfma_scale_f32_16x16x128_f8f6f4 v[112:115], v[24:31], v[210:217], v[112:115], v180, v180 op_sel_hi:[0,0,0]
	v_mfma_scale_f32_16x16x128_f8f6f4 v[104:107], v[16:23], v[210:217], v[104:107], v180, v180 op_sel_hi:[0,0,0]
	s_setprio 0
	s_setprio 3
	v_mfma_scale_f32_16x16x128_f8f6f4 v[148:151], v[8:15], v[172:179], v[148:151], v180, v180 op_sel_hi:[0,0,0]
	v_mfma_scale_f32_16x16x128_f8f6f4 v[140:143], v[0:7], v[172:179], v[140:143], v180, v180 op_sel_hi:[0,0,0]
	v_mfma_scale_f32_16x16x128_f8f6f4 v[132:135], v[8:15], v[186:193], v[132:135], v180, v180 op_sel_hi:[0,0,0]
	v_mfma_scale_f32_16x16x128_f8f6f4 v[124:127], v[0:7], v[186:193], v[124:127], v180, v180 op_sel_hi:[0,0,0]
	v_mfma_scale_f32_16x16x128_f8f6f4 v[116:119], v[8:15], v[194:201], v[116:119], v180, v180 op_sel_hi:[0,0,0]
	v_mfma_scale_f32_16x16x128_f8f6f4 v[108:111], v[0:7], v[194:201], v[108:111], v180, v180 op_sel_hi:[0,0,0]
	v_mfma_scale_f32_16x16x128_f8f6f4 v[100:103], v[8:15], v[210:217], v[100:103], v180, v180 op_sel_hi:[0,0,0]
	v_mfma_scale_f32_16x16x128_f8f6f4 v[96:99], v[0:7], v[210:217], v[96:99], v180, v180 op_sel_hi:[0,0,0]
	s_barrier
	s_setprio 0
	s_add_i32 s0, s65, s58
	v_lshl_add_u64 v[172:173], s[52:53], 0, v[162:163]
	s_mov_b32 m0, s0
	ds_read_b128 v[186:189], v184 offset:16384
	ds_read_b128 v[190:193], v184 offset:17408
	ds_read_b128 v[194:197], v184 offset:18432
	ds_read_b128 v[198:201], v184 offset:19456
	ds_read_b128 v[210:213], v184 offset:20480
	ds_read_b128 v[214:217], v184 offset:21504
	ds_read_b128 v[218:221], v184 offset:22528
	ds_read_b128 v[222:225], v184 offset:23552
	global_load_lds_dwordx4 v[172:173], off
	s_add_i32 m0, s0, 0x2000
	s_add_u32 s0, s52, 0x80000
	v_lshl_add_u64 v[174:175], s[52:53], 0, v[166:167]
	s_addc_u32 s1, s53, 0
	s_add_i32 s37, s66, s58
	global_load_lds_dwordx4 v[174:175], off
	s_mov_b32 m0, s37
	v_lshl_add_u64 v[178:179], s[54:55], 0, v[164:165]
	global_load_lds_dwordx4 v162, s[0:1]
	s_add_i32 m0, s37, 0x2000
	s_nop 0
	global_load_lds_dwordx4 v166, s[0:1]
	v_lshl_add_u64 v[176:177], s[54:55], 0, v[160:161]
	s_mov_b32 m0, s43
	s_nop 0
	global_load_lds_dwordx4 v[176:177], off
	s_mov_b32 m0, s59
	s_nop 0
	global_load_lds_dwordx4 v[178:179], off
	s_waitcnt vmcnt(8)
	s_waitcnt lgkmcnt(0)
	s_setprio 3
	s_barrier
	v_mfma_scale_f32_16x16x128_f8f6f4 v[92:95], v[24:31], v[186:193], v[92:95], v180, v180 op_sel_hi:[0,0,0]
	v_mfma_scale_f32_16x16x128_f8f6f4 v[88:91], v[16:23], v[186:193], v[88:91], v180, v180 op_sel_hi:[0,0,0]
	v_mfma_scale_f32_16x16x128_f8f6f4 v[80:83], v[24:31], v[194:201], v[80:83], v180, v180 op_sel_hi:[0,0,0]
	v_mfma_scale_f32_16x16x128_f8f6f4 v[72:75], v[16:23], v[194:201], v[72:75], v180, v180 op_sel_hi:[0,0,0]
	v_mfma_scale_f32_16x16x128_f8f6f4 v[64:67], v[24:31], v[210:217], v[64:67], v180, v180 op_sel_hi:[0,0,0]
	v_mfma_scale_f32_16x16x128_f8f6f4 v[56:59], v[16:23], v[210:217], v[56:59], v180, v180 op_sel_hi:[0,0,0]
	v_mfma_scale_f32_16x16x128_f8f6f4 v[48:51], v[24:31], v[218:225], v[48:51], v180, v180 op_sel_hi:[0,0,0]
	v_mfma_scale_f32_16x16x128_f8f6f4 v[40:43], v[16:23], v[218:225], v[40:43], v180, v180 op_sel_hi:[0,0,0]
	s_setprio 0
	s_setprio 3
	v_mfma_scale_f32_16x16x128_f8f6f4 v[84:87], v[8:15], v[186:193], v[84:87], v180, v180 op_sel_hi:[0,0,0]
	v_mfma_scale_f32_16x16x128_f8f6f4 v[76:79], v[0:7], v[186:193], v[76:79], v180, v180 op_sel_hi:[0,0,0]
	v_mfma_scale_f32_16x16x128_f8f6f4 v[68:71], v[8:15], v[194:201], v[68:71], v180, v180 op_sel_hi:[0,0,0]
	v_mfma_scale_f32_16x16x128_f8f6f4 v[60:63], v[0:7], v[194:201], v[60:63], v180, v180 op_sel_hi:[0,0,0]
	v_mfma_scale_f32_16x16x128_f8f6f4 v[52:55], v[8:15], v[210:217], v[52:55], v180, v180 op_sel_hi:[0,0,0]
	v_mfma_scale_f32_16x16x128_f8f6f4 v[44:47], v[0:7], v[210:217], v[44:47], v180, v180 op_sel_hi:[0,0,0]
	v_mfma_scale_f32_16x16x128_f8f6f4 v[36:39], v[8:15], v[218:225], v[36:39], v180, v180 op_sel_hi:[0,0,0]
	v_mfma_scale_f32_16x16x128_f8f6f4 v[32:35], v[0:7], v[218:225], v[32:35], v180, v180 op_sel_hi:[0,0,0]
	s_barrier
	s_setprio 0
	s_add_i32 s37, 0, 0x18000
	s_add_i32 s56, 0, 0x1c000
	v_add_u32_e32 v12, s37, v182
	v_add_u32_e32 v28, s56, v182
	ds_read_b128 v[0:3], v12
	ds_read_b128 v[4:7], v12 offset:1024
	ds_read_b128 v[8:11], v12 offset:2048
	ds_read_b128 v[12:15], v12 offset:3072
	ds_read_b128 v[16:19], v28
	ds_read_b128 v[20:23], v28 offset:1024
	ds_read_b128 v[24:27], v28 offset:2048
	ds_read_b128 v[28:31], v28 offset:3072
	s_add_u32 s0, s54, 0x80000
	s_addc_u32 s1, s55, 0
	s_mov_b32 m0, s60
	ds_read_b128 v[186:189], v184 offset:32768
	ds_read_b128 v[190:193], v184 offset:33792
	ds_read_b128 v[194:197], v184 offset:34816
	ds_read_b128 v[198:201], v184 offset:35840
	ds_read_b128 v[210:213], v184 offset:36864
	ds_read_b128 v[214:217], v184 offset:37888
	ds_read_b128 v[218:221], v184 offset:38912
	ds_read_b128 v[222:225], v184 offset:39936
	global_load_lds_dwordx4 v160, s[0:1]
	s_mov_b32 m0, s61
	s_nop 0
	global_load_lds_dwordx4 v164, s[0:1]
	s_waitcnt vmcnt(8)
	s_waitcnt lgkmcnt(0)
	s_setprio 3
	s_barrier
	v_mfma_scale_f32_16x16x128_f8f6f4 v[156:159], v[0:7], v[186:193], v[156:159], v180, v180 op_sel_hi:[0,0,0]
	v_mfma_scale_f32_16x16x128_f8f6f4 v[152:155], v[8:15], v[186:193], v[152:155], v180, v180 op_sel_hi:[0,0,0]
	v_mfma_scale_f32_16x16x128_f8f6f4 v[144:147], v[0:7], v[194:201], v[144:147], v180, v180 op_sel_hi:[0,0,0]
	v_mfma_scale_f32_16x16x128_f8f6f4 v[136:139], v[8:15], v[194:201], v[136:139], v180, v180 op_sel_hi:[0,0,0]
	v_mfma_scale_f32_16x16x128_f8f6f4 v[128:131], v[0:7], v[210:217], v[128:131], v180, v180 op_sel_hi:[0,0,0]
	v_mfma_scale_f32_16x16x128_f8f6f4 v[120:123], v[8:15], v[210:217], v[120:123], v180, v180 op_sel_hi:[0,0,0]
	v_mfma_scale_f32_16x16x128_f8f6f4 v[112:115], v[0:7], v[218:225], v[112:115], v180, v180 op_sel_hi:[0,0,0]
	v_mfma_scale_f32_16x16x128_f8f6f4 v[104:107], v[8:15], v[218:225], v[104:107], v180, v180 op_sel_hi:[0,0,0]
	s_setprio 0
	s_setprio 3
	v_mfma_scale_f32_16x16x128_f8f6f4 v[148:151], v[16:23], v[186:193], v[148:151], v180, v180 op_sel_hi:[0,0,0]
	v_mfma_scale_f32_16x16x128_f8f6f4 v[140:143], v[24:31], v[186:193], v[140:143], v180, v180 op_sel_hi:[0,0,0]
	v_mfma_scale_f32_16x16x128_f8f6f4 v[132:135], v[16:23], v[194:201], v[132:135], v180, v180 op_sel_hi:[0,0,0]
	v_mfma_scale_f32_16x16x128_f8f6f4 v[124:127], v[24:31], v[194:201], v[124:127], v180, v180 op_sel_hi:[0,0,0]
	v_mfma_scale_f32_16x16x128_f8f6f4 v[116:119], v[16:23], v[210:217], v[116:119], v180, v180 op_sel_hi:[0,0,0]
	v_mfma_scale_f32_16x16x128_f8f6f4 v[108:111], v[24:31], v[210:217], v[108:111], v180, v180 op_sel_hi:[0,0,0]
	v_mfma_scale_f32_16x16x128_f8f6f4 v[100:103], v[16:23], v[218:225], v[100:103], v180, v180 op_sel_hi:[0,0,0]
	v_mfma_scale_f32_16x16x128_f8f6f4 v[96:99], v[24:31], v[218:225], v[96:99], v180, v180 op_sel_hi:[0,0,0]
	s_barrier
	s_setprio 0
	s_add_i32 s0, s37, s58
	v_lshl_add_u64 v[172:173], v[172:173], 0, s[12:13]
	s_mov_b32 m0, s0
	ds_read_b128 v[186:189], v184 offset:49152
	ds_read_b128 v[190:193], v184 offset:50176
	ds_read_b128 v[194:197], v184 offset:51200
	ds_read_b128 v[198:201], v184 offset:52224
	ds_read_b128 v[210:213], v184 offset:53248
	ds_read_b128 v[214:217], v184 offset:54272
	ds_read_b128 v[218:221], v184 offset:55296
	ds_read_b128 v[222:225], v184 offset:56320
	global_load_lds_dwordx4 v[172:173], off
	s_add_i32 m0, s0, 0x2000
	s_add_u32 s0, s52, 0x80080
	v_lshl_add_u64 v[172:173], v[174:175], 0, s[12:13]
	s_addc_u32 s1, s53, 0
	s_add_i32 s37, s56, s58
	global_load_lds_dwordx4 v[172:173], off
	s_mov_b32 m0, s37
	s_nop 0
	global_load_lds_dwordx4 v162, s[0:1]
	s_add_i32 m0, s37, 0x2000
	s_nop 0
	global_load_lds_dwordx4 v166, s[0:1]
	v_lshl_add_u64 v[172:173], v[176:177], 0, s[12:13]
	s_mov_b32 m0, s62
	s_nop 0
	global_load_lds_dwordx4 v[172:173], off
	v_lshl_add_u64 v[172:173], v[178:179], 0, s[12:13]
	s_mov_b32 m0, s63
	s_nop 0
	global_load_lds_dwordx4 v[172:173], off
	s_waitcnt vmcnt(8)
	s_waitcnt lgkmcnt(0)
	s_setprio 3
	s_barrier
	v_mfma_scale_f32_16x16x128_f8f6f4 v[92:95], v[0:7], v[186:193], v[92:95], v180, v180 op_sel_hi:[0,0,0]
	v_mfma_scale_f32_16x16x128_f8f6f4 v[88:91], v[8:15], v[186:193], v[88:91], v180, v180 op_sel_hi:[0,0,0]
	v_mfma_scale_f32_16x16x128_f8f6f4 v[80:83], v[0:7], v[194:201], v[80:83], v180, v180 op_sel_hi:[0,0,0]
	v_mfma_scale_f32_16x16x128_f8f6f4 v[72:75], v[8:15], v[194:201], v[72:75], v180, v180 op_sel_hi:[0,0,0]
	v_mfma_scale_f32_16x16x128_f8f6f4 v[64:67], v[0:7], v[210:217], v[64:67], v180, v180 op_sel_hi:[0,0,0]
	v_mfma_scale_f32_16x16x128_f8f6f4 v[56:59], v[8:15], v[210:217], v[56:59], v180, v180 op_sel_hi:[0,0,0]
	v_mfma_scale_f32_16x16x128_f8f6f4 v[48:51], v[0:7], v[218:225], v[48:51], v180, v180 op_sel_hi:[0,0,0]
	v_mfma_scale_f32_16x16x128_f8f6f4 v[40:43], v[8:15], v[218:225], v[40:43], v180, v180 op_sel_hi:[0,0,0]
	s_setprio 0
	s_setprio 3
	v_mfma_scale_f32_16x16x128_f8f6f4 v[84:87], v[16:23], v[186:193], v[84:87], v180, v180 op_sel_hi:[0,0,0]
	v_mfma_scale_f32_16x16x128_f8f6f4 v[76:79], v[24:31], v[186:193], v[76:79], v180, v180 op_sel_hi:[0,0,0]
	v_mfma_scale_f32_16x16x128_f8f6f4 v[68:71], v[16:23], v[194:201], v[68:71], v180, v180 op_sel_hi:[0,0,0]
	v_mfma_scale_f32_16x16x128_f8f6f4 v[60:63], v[24:31], v[194:201], v[60:63], v180, v180 op_sel_hi:[0,0,0]
	v_mfma_scale_f32_16x16x128_f8f6f4 v[52:55], v[16:23], v[210:217], v[52:55], v180, v180 op_sel_hi:[0,0,0]
	v_mfma_scale_f32_16x16x128_f8f6f4 v[44:47], v[24:31], v[210:217], v[44:47], v180, v180 op_sel_hi:[0,0,0]
	v_mfma_scale_f32_16x16x128_f8f6f4 v[36:39], v[16:23], v[218:225], v[36:39], v180, v180 op_sel_hi:[0,0,0]
	v_mfma_scale_f32_16x16x128_f8f6f4 v[32:35], v[24:31], v[218:225], v[32:35], v180, v180 op_sel_hi:[0,0,0]
	s_barrier
	s_setprio 0
	s_cmpk_gt_u32 s35, 0x53
	s_mov_b32 s37, s6
	s_cbranch_scc1 .LBB0_1981
